# P2 attention units dealt per block class (plain blocks take the heaviest 480, g2 blocks the next 512, chunk-0 GLA blocks the 32 lightest); on top of v20
# speedup vs baseline: 1.0193x; 1.0020x over previous
.LBB0_624:
	s_cmp_lg_u32 s96, 0x100
	s_cbranch_scc1 .Lp2_dflt
	s_cmp_lt_u32 s89, 4
	s_cbranch_scc1 .Lp2_r03
	s_add_i32 s13, s2, 0x380
	s_add_i32 s100, s2, 0xffffff80
	s_cmp_lt_u32 s100, 16
	s_cselect_b32 s13, s13, 0x7ff
	s_cmp_eq_u32 s89, 4
	s_cselect_b32 s13, s13, 0x7ff
	s_branch .Lp2_dflt
.Lp2_r03:
	s_cmp_lt_u32 s2, 8
	s_cbranch_scc0 .Lp2_ge8
	s_lshl_b32 s13, s2, 2
	s_add_i32 s13, s13, s89
	s_addk_i32 s13, 0x3e0
	s_branch .Lp2_dflt
.Lp2_ge8:
	s_movk_i32 s100, 0x80
	s_movk_i32 s101, 0x80
	s_cmp_lt_u32 s2, 0x80
	s_cmovk_i32 s100, 0x78
	s_cmovk_i32 s101, 8
	s_sub_i32 s101, s2, s101
	s_mul_i32 s13, s89, s100
	s_add_i32 s13, s13, s101
	s_add_i32 s20, s89, 1
	s_mul_i32 s20, s20, s100
	s_sub_i32 s20, s20, s101
	s_add_i32 s20, s20, -1
	s_bitcmp1_b32 s89, 0
	s_cselect_b32 s13, s20, s13
	s_cmp_lt_u32 s2, 0x80
	s_cselect_b32 s20, 0, 0x1e0
	s_add_i32 s13, s13, s20
